# prep reads the DONE counters with single-lane returning atomics (fresh values) + R3 shifted-V loads batched
# speedup vs baseline: 1.0223x; 1.0130x over previous
; __device__ void phase_rwkv_dist(const Params& p, LAS unsigned char* lds, int wg, int nwg) {
;     ...
;                 if (ci >= RD_NG) { unsigned sp = 0; while (!dead && __hip_atomic_load(DONE + bh * 512 + (ci - RD_NG), __ATOMIC_RELAXED, __HIP_MEMORY_SCOPE_AGENT) < 256u) { __builtin_amdgcn_s_sleep(2); if (++sp > RD_SPIN_MAX) { if (lane == 0) atomicAdd(ERR, 1u); dead = true; } } }
.Lprep_nopend:
	v_readfirstlane_b32 s81, v252
	s_cmp_ge_u32 s81, s49
	s_cselect_b64 s[92:93], -1, 0
	v_mov_b64_e32 v[60:61], v[220:221]
	v_mov_b64_e32 v[62:63], v[222:223]
	v_mov_b64_e32 v[112:113], v[224:225]
	v_mov_b64_e32 v[94:95], v[226:227]
	v_mov_b64_e32 v[64:65], v[228:229]
	v_mov_b64_e32 v[66:67], v[230:231]
	v_mov_b64_e32 v[114:115], v[232:233]
	v_mov_b64_e32 v[96:97], v[234:235]
	v_mov_b64_e32 v[118:119], v[236:237]
	v_mov_b64_e32 v[104:105], v[238:239]
	v_mov_b64_e32 v[100:101], v[240:241]
	v_mov_b64_e32 v[108:109], v[242:243]
	v_mov_b64_e32 v[120:121], v[244:245]
	v_mov_b64_e32 v[106:107], v[246:247]
	v_mov_b64_e32 v[102:103], v[248:249]
	v_mov_b64_e32 v[110:111], v[250:251]
	s_cmpk_gt_i32 s2, 0x1ff
	s_cbranch_scc1 .LBB0_656
	s_lshl_b32 s85, s2, 11
	s_add_i32 s85, s85, s18
	s_cmp_lt_i32 s2, 56
	s_cbranch_scc1 .Lprep_nopoll
	s_lshl_b32 s86, s2, 2
	s_add_u32 s86, s19, s86
	s_addc_u32 s87, s40, 0
	s_mov_b64 s[82:83], exec
	s_mov_b64 exec, 1
	global_atomic_add v252, v1, v1, s[86:87] offset:-224 sc0
	s_mov_b64 exec, s[82:83]

; __device__ void phase_rwkv_dist(const Params& p, LAS unsigned char* lds, int wg, int nwg) {
;     ...
;                 if (ci >= RD_NG) { unsigned sp = 0; while (!dead && __hip_atomic_load(DONE + bh * 512 + (ci - RD_NG), __ATOMIC_RELAXED, __HIP_MEMORY_SCOPE_AGENT) < 256u) { __builtin_amdgcn_s_sleep(2); if (++sp > RD_SPIN_MAX) { if (lane == 0) atomicAdd(ERR, 1u); dead = true; } } }
.LBB0_660:
	s_mov_b64 s[82:83], exec
	s_mov_b64 exec, 1
	global_atomic_add v101, v1, v1, s[2:3] offset:-224 sc0
	s_mov_b64 exec, s[82:83]
	s_movk_i32 s0, 0xff
	s_waitcnt vmcnt(0)
	v_readfirstlane_b32 s81, v101
	s_cmp_ge_u32 s81, s49
	s_cbranch_scc1 .LBB0_659
	s_sleep 2
	s_mov_b64 s[82:83], exec
	s_mov_b64 exec, 1
	global_atomic_add v101, v1, v1, s[2:3] offset:-224 sc0
	s_mov_b64 exec, s[82:83]
	s_waitcnt vmcnt(0)
	v_readfirstlane_b32 s81, v101
	s_cmp_ge_u32 s81, s49
	s_cbranch_scc1 .LBB0_659
	s_sleep 2
	s_mov_b64 s[82:83], exec
	s_mov_b64 exec, 1
	global_atomic_add v101, v1, v1, s[2:3] offset:-224 sc0
	s_mov_b64 exec, s[82:83]
	s_waitcnt vmcnt(0)
	v_readfirstlane_b32 s81, v101
	s_cmp_ge_u32 s81, s49
	s_cbranch_scc1 .LBB0_659
	s_cmp_gt_u32 s44, 0x7fffd
	s_cselect_b64 s[0:1], -1, 0
	s_and_b64 s[6:7], s[4:5], s[0:1]
	s_sleep 2
	s_and_saveexec_b64 s[0:1], s[6:7]
	s_cbranch_execz .LBB0_666
	s_mov_b64 s[6:7], exec
	v_mbcnt_lo_u32_b32 v101, s6, 0
	v_mbcnt_hi_u32_b32 v101, s7, v101
	v_cmp_eq_u32_e32 vcc, 0, v101
	s_and_b64 s[46:47], exec, vcc
	s_mov_b64 exec, s[46:47]
	s_cbranch_execz .LBB0_666
	s_bcnt1_i32_b64 s6, s[6:7]
	v_mov_b32_e32 v101, s6
	global_atomic_add v1, v101, s[96:97]
